# code placement: MFMA loop heads padded back to hipcc's original byte phase (mod 8)
# speedup vs baseline: 1.0073x; 1.0073x over previous
.Lh9_b:
	s_ashr_i32 s47, s46, 31
	s_lshl_b64 s[18:19], s[46:47], 19
	s_add_u32 s54, s22, s18
	v_mov_b32_e32 v129, 0
	s_addc_u32 s55, s23, s19
	s_andn2_b64 vcc, exec, s[34:35]
	s_cbranch_vccnz .LBB0_255
	s_and_b64 s[18:19], s[42:43], exec
	s_cselect_b32 s47, s51, s57
	s_cselect_b32 s49, s50, s56
	s_cselect_b32 s72, s55, s27
	s_cselect_b32 s73, s54, s26
	s_add_u32 s78, s56, 0x100
	s_addc_u32 s79, s57, 0
	s_add_u32 s80, s26, 0x100
	v_mov_b32_e32 v2, 0
	s_addc_u32 s81, s27, 0
	s_mov_b32 s18, 0
	v_mov_b32_e32 v3, v2
	v_mov_b32_e32 v4, v2
	v_mov_b32_e32 v5, v2
	v_mov_b32_e32 v6, v2
	v_mov_b32_e32 v7, v2
	v_mov_b32_e32 v8, v2
	v_mov_b32_e32 v9, v2
	v_mov_b32_e32 v18, v2
	v_mov_b32_e32 v19, v2
	v_mov_b32_e32 v20, v2
	v_mov_b32_e32 v21, v2
	v_mov_b32_e32 v22, v2
	v_mov_b32_e32 v23, v2
	v_mov_b32_e32 v24, v2
	v_mov_b32_e32 v25, v2
	v_mov_b32_e32 v34, v2
	v_mov_b32_e32 v35, v2
	v_mov_b32_e32 v36, v2
	v_mov_b32_e32 v37, v2
	v_mov_b32_e32 v38, v2
	v_mov_b32_e32 v39, v2
	v_mov_b32_e32 v40, v2
	v_mov_b32_e32 v41, v2
	v_mov_b32_e32 v50, v2
	v_mov_b32_e32 v51, v2
	v_mov_b32_e32 v52, v2
	v_mov_b32_e32 v53, v2
	v_mov_b32_e32 v54, v2
	v_mov_b32_e32 v55, v2
	v_mov_b32_e32 v56, v2
	v_mov_b32_e32 v57, v2
	v_mov_b32_e32 v10, v2
	v_mov_b32_e32 v11, v2
	v_mov_b32_e32 v12, v2
	v_mov_b32_e32 v13, v2
	v_mov_b32_e32 v14, v2
	v_mov_b32_e32 v15, v2
	v_mov_b32_e32 v16, v2
	v_mov_b32_e32 v17, v2
	v_mov_b32_e32 v26, v2
	v_mov_b32_e32 v27, v2
	v_mov_b32_e32 v28, v2
	v_mov_b32_e32 v29, v2
	v_mov_b32_e32 v30, v2
	v_mov_b32_e32 v31, v2
	v_mov_b32_e32 v32, v2
	v_mov_b32_e32 v33, v2
	v_mov_b32_e32 v42, v2
	v_mov_b32_e32 v43, v2
	v_mov_b32_e32 v44, v2
	v_mov_b32_e32 v45, v2
	v_mov_b32_e32 v46, v2
	v_mov_b32_e32 v47, v2
	v_mov_b32_e32 v48, v2
	v_mov_b32_e32 v49, v2
	v_mov_b32_e32 v58, v2
	v_mov_b32_e32 v59, v2
	v_mov_b32_e32 v60, v2
	v_mov_b32_e32 v61, v2
	v_mov_b32_e32 v62, v2
	v_mov_b32_e32 v63, v2
	v_mov_b32_e32 v64, v2
	v_mov_b32_e32 v65, v2
	v_mov_b32_e32 v66, v2
	v_mov_b32_e32 v67, v2
	v_mov_b32_e32 v68, v2
	v_mov_b32_e32 v69, v2
	v_mov_b32_e32 v70, v2
	v_mov_b32_e32 v71, v2
	v_mov_b32_e32 v72, v2
	v_mov_b32_e32 v73, v2
	v_mov_b32_e32 v82, v2
	v_mov_b32_e32 v83, v2
	v_mov_b32_e32 v84, v2
	v_mov_b32_e32 v85, v2
	v_mov_b32_e32 v86, v2
	v_mov_b32_e32 v87, v2
	v_mov_b32_e32 v88, v2
	v_mov_b32_e32 v89, v2
	v_mov_b32_e32 v98, v2
	v_mov_b32_e32 v99, v2
	v_mov_b32_e32 v100, v2
	v_mov_b32_e32 v101, v2
	v_mov_b32_e32 v102, v2
	v_mov_b32_e32 v103, v2
	v_mov_b32_e32 v104, v2
	v_mov_b32_e32 v105, v2
	v_mov_b32_e32 v114, v2
	v_mov_b32_e32 v115, v2
	v_mov_b32_e32 v116, v2
	v_mov_b32_e32 v117, v2
	v_mov_b32_e32 v118, v2
	v_mov_b32_e32 v119, v2
	v_mov_b32_e32 v120, v2
	v_mov_b32_e32 v121, v2
	v_mov_b32_e32 v74, v2
	v_mov_b32_e32 v75, v2
	v_mov_b32_e32 v76, v2
	v_mov_b32_e32 v77, v2
	v_mov_b32_e32 v78, v2
	v_mov_b32_e32 v79, v2
	v_mov_b32_e32 v80, v2
	v_mov_b32_e32 v81, v2
	v_mov_b32_e32 v90, v2
	v_mov_b32_e32 v91, v2
	v_mov_b32_e32 v92, v2
	v_mov_b32_e32 v93, v2
	v_mov_b32_e32 v94, v2
	v_mov_b32_e32 v95, v2
	v_mov_b32_e32 v96, v2
	v_mov_b32_e32 v97, v2
	v_mov_b32_e32 v106, v2
	v_mov_b32_e32 v107, v2
	v_mov_b32_e32 v108, v2
	v_mov_b32_e32 v109, v2
	v_mov_b32_e32 v110, v2
	v_mov_b32_e32 v111, v2
	v_mov_b32_e32 v112, v2
	v_mov_b32_e32 v113, v2
	v_mov_b32_e32 v122, v2
	v_mov_b32_e32 v123, v2
	v_mov_b32_e32 v124, v2
	v_mov_b32_e32 v125, v2
	v_mov_b32_e32 v126, v2
	v_mov_b32_e32 v127, v2
	v_mov_b32_e32 v128, v2
	v_mov_b32_e32 v129, v2
	s_nop 0

.LBB0_438:
	s_ashr_i32 s61, s60, 31
	s_lshl_b64 s[18:19], s[60:61], 18
	s_add_u32 s62, s17, s18
	s_addc_u32 s63, s21, s19
	s_ashr_i32 s55, s54, 31
	s_lshl_b64 s[18:19], s[54:55], 18
	s_add_u32 s36, s22, s18
	v_mov_b32_e32 v129, 0
	s_addc_u32 s37, s23, s19
	s_andn2_b64 vcc, exec, s[30:31]
	s_cbranch_vccnz .LBB0_442
	s_and_b64 s[18:19], s[42:43], exec
	s_cselect_b32 s1, s63, s45
	s_cselect_b32 s3, s62, s44
	s_cselect_b32 s40, s37, s27
	s_cselect_b32 s41, s36, s26
	s_add_u32 s55, s44, 0x100
	s_addc_u32 s61, s45, 0
	s_add_u32 s80, s26, 0x100
	v_mov_b32_e32 v2, 0
	s_addc_u32 s81, s27, 0
	s_mov_b32 s18, 0
	v_mov_b32_e32 v3, v2
	v_mov_b32_e32 v4, v2
	v_mov_b32_e32 v5, v2
	v_mov_b32_e32 v6, v2
	v_mov_b32_e32 v7, v2
	v_mov_b32_e32 v8, v2
	v_mov_b32_e32 v9, v2
	v_mov_b32_e32 v10, v2
	v_mov_b32_e32 v11, v2
	v_mov_b32_e32 v12, v2
	v_mov_b32_e32 v13, v2
	v_mov_b32_e32 v14, v2
	v_mov_b32_e32 v15, v2
	v_mov_b32_e32 v16, v2
	v_mov_b32_e32 v17, v2
	v_mov_b32_e32 v18, v2
	v_mov_b32_e32 v19, v2
	v_mov_b32_e32 v20, v2
	v_mov_b32_e32 v21, v2
	v_mov_b32_e32 v22, v2
	v_mov_b32_e32 v23, v2
	v_mov_b32_e32 v24, v2
	v_mov_b32_e32 v25, v2
	v_mov_b32_e32 v26, v2
	v_mov_b32_e32 v27, v2
	v_mov_b32_e32 v28, v2
	v_mov_b32_e32 v29, v2
	v_mov_b32_e32 v30, v2
	v_mov_b32_e32 v31, v2
	v_mov_b32_e32 v32, v2
	v_mov_b32_e32 v33, v2
	v_mov_b32_e32 v66, v2
	v_mov_b32_e32 v67, v2
	v_mov_b32_e32 v68, v2
	v_mov_b32_e32 v69, v2
	v_mov_b32_e32 v70, v2
	v_mov_b32_e32 v71, v2
	v_mov_b32_e32 v72, v2
	v_mov_b32_e32 v73, v2
	v_mov_b32_e32 v74, v2
	v_mov_b32_e32 v75, v2
	v_mov_b32_e32 v76, v2
	v_mov_b32_e32 v77, v2
	v_mov_b32_e32 v78, v2
	v_mov_b32_e32 v79, v2
	v_mov_b32_e32 v80, v2
	v_mov_b32_e32 v81, v2
	v_mov_b32_e32 v82, v2
	v_mov_b32_e32 v83, v2
	v_mov_b32_e32 v84, v2
	v_mov_b32_e32 v85, v2
	v_mov_b32_e32 v86, v2
	v_mov_b32_e32 v87, v2
	v_mov_b32_e32 v88, v2
	v_mov_b32_e32 v89, v2
	v_mov_b32_e32 v90, v2
	v_mov_b32_e32 v91, v2
	v_mov_b32_e32 v92, v2
	v_mov_b32_e32 v93, v2
	v_mov_b32_e32 v94, v2
	v_mov_b32_e32 v95, v2
	v_mov_b32_e32 v96, v2
	v_mov_b32_e32 v97, v2
	v_mov_b32_e32 v34, v2
	v_mov_b32_e32 v35, v2
	v_mov_b32_e32 v36, v2
	v_mov_b32_e32 v37, v2
	v_mov_b32_e32 v38, v2
	v_mov_b32_e32 v39, v2
	v_mov_b32_e32 v40, v2
	v_mov_b32_e32 v41, v2
	v_mov_b32_e32 v42, v2
	v_mov_b32_e32 v43, v2
	v_mov_b32_e32 v44, v2
	v_mov_b32_e32 v45, v2
	v_mov_b32_e32 v46, v2
	v_mov_b32_e32 v47, v2
	v_mov_b32_e32 v48, v2
	v_mov_b32_e32 v49, v2
	v_mov_b32_e32 v50, v2
	v_mov_b32_e32 v51, v2
	v_mov_b32_e32 v52, v2
	v_mov_b32_e32 v53, v2
	v_mov_b32_e32 v54, v2
	v_mov_b32_e32 v55, v2
	v_mov_b32_e32 v56, v2
	v_mov_b32_e32 v57, v2
	v_mov_b32_e32 v58, v2
	v_mov_b32_e32 v59, v2
	v_mov_b32_e32 v60, v2
	v_mov_b32_e32 v61, v2
	v_mov_b32_e32 v62, v2
	v_mov_b32_e32 v63, v2
	v_mov_b32_e32 v64, v2
	v_mov_b32_e32 v65, v2
	v_mov_b32_e32 v98, v2
	v_mov_b32_e32 v99, v2
	v_mov_b32_e32 v100, v2
	v_mov_b32_e32 v101, v2
	v_mov_b32_e32 v102, v2
	v_mov_b32_e32 v103, v2
	v_mov_b32_e32 v104, v2
	v_mov_b32_e32 v105, v2
	v_mov_b32_e32 v106, v2
	v_mov_b32_e32 v107, v2
	v_mov_b32_e32 v108, v2
	v_mov_b32_e32 v109, v2
	v_mov_b32_e32 v110, v2
	v_mov_b32_e32 v111, v2
	v_mov_b32_e32 v112, v2
	v_mov_b32_e32 v113, v2
	v_mov_b32_e32 v114, v2
	v_mov_b32_e32 v115, v2
	v_mov_b32_e32 v116, v2
	v_mov_b32_e32 v117, v2
	v_mov_b32_e32 v118, v2
	v_mov_b32_e32 v119, v2
	v_mov_b32_e32 v120, v2
	v_mov_b32_e32 v121, v2
	v_mov_b32_e32 v122, v2
	v_mov_b32_e32 v123, v2
	v_mov_b32_e32 v124, v2
	v_mov_b32_e32 v125, v2
	v_mov_b32_e32 v126, v2
	v_mov_b32_e32 v127, v2
	v_mov_b32_e32 v128, v2
	v_mov_b32_e32 v129, v2
	s_nop 0

.LBB0_510:
	s_ashr_i32 s55, s54, 31
	s_lshl_b64 s[18:19], s[54:55], 17
	s_cmp_eq_u32 s70, 0
	s_cselect_b32 s55, s30, s2
	s_cselect_b32 s51, s31, s3
	s_cselect_b32 s61, s1, s31
	s_cselect_b32 s60, s0, s30
	s_add_u32 s56, s55, s18
	s_addc_u32 s57, s51, s19
	s_ashr_i32 s51, s50, 31
	s_lshl_b64 s[18:19], s[50:51], 17
	s_add_u32 s60, s60, s18
	v_mov_b32_e32 v125, 0
	s_addc_u32 s61, s61, s19
	s_andn2_b64 vcc, exec, s[36:37]
	s_cbranch_vccnz .LBB0_514
	s_and_b64 s[18:19], s[42:43], exec
	s_cselect_b32 s51, s57, s63
	s_cselect_b32 s55, s56, s62
	s_cselect_b32 s72, s61, s27
	s_cselect_b32 s73, s60, s26
	s_add_u32 s78, s62, 0x100
	s_addc_u32 s79, s63, 0
	s_add_u32 s80, s26, 0x100
	v_mov_b32_e32 v2, 0
	s_addc_u32 s81, s27, 0
	s_mov_b32 s18, 0
	v_mov_b32_e32 v3, v2
	v_mov_b32_e32 v4, v2
	v_mov_b32_e32 v5, v2
	v_mov_b32_e32 v6, v2
	v_mov_b32_e32 v7, v2
	v_mov_b32_e32 v8, v2
	v_mov_b32_e32 v9, v2
	v_mov_b32_e32 v18, v2
	v_mov_b32_e32 v19, v2
	v_mov_b32_e32 v20, v2
	v_mov_b32_e32 v21, v2
	v_mov_b32_e32 v22, v2
	v_mov_b32_e32 v23, v2
	v_mov_b32_e32 v24, v2
	v_mov_b32_e32 v25, v2
	v_mov_b32_e32 v34, v2
	v_mov_b32_e32 v35, v2
	v_mov_b32_e32 v36, v2
	v_mov_b32_e32 v37, v2
	v_mov_b32_e32 v38, v2
	v_mov_b32_e32 v39, v2
	v_mov_b32_e32 v40, v2
	v_mov_b32_e32 v41, v2
	v_mov_b32_e32 v50, v2
	v_mov_b32_e32 v51, v2
	v_mov_b32_e32 v52, v2
	v_mov_b32_e32 v53, v2
	v_mov_b32_e32 v54, v2
	v_mov_b32_e32 v55, v2
	v_mov_b32_e32 v56, v2
	v_mov_b32_e32 v57, v2
	v_mov_b32_e32 v10, v2
	v_mov_b32_e32 v11, v2
	v_mov_b32_e32 v12, v2
	v_mov_b32_e32 v13, v2
	v_mov_b32_e32 v14, v2
	v_mov_b32_e32 v15, v2
	v_mov_b32_e32 v16, v2
	v_mov_b32_e32 v17, v2
	v_mov_b32_e32 v26, v2
	v_mov_b32_e32 v27, v2
	v_mov_b32_e32 v28, v2
	v_mov_b32_e32 v29, v2
	v_mov_b32_e32 v30, v2
	v_mov_b32_e32 v31, v2
	v_mov_b32_e32 v32, v2
	v_mov_b32_e32 v33, v2
	v_mov_b32_e32 v42, v2
	v_mov_b32_e32 v43, v2
	v_mov_b32_e32 v44, v2
	v_mov_b32_e32 v45, v2
	v_mov_b32_e32 v46, v2
	v_mov_b32_e32 v47, v2
	v_mov_b32_e32 v48, v2
	v_mov_b32_e32 v49, v2
	v_mov_b32_e32 v58, v2
	v_mov_b32_e32 v59, v2
	v_mov_b32_e32 v60, v2
	v_mov_b32_e32 v61, v2
	v_mov_b32_e32 v62, v2
	v_mov_b32_e32 v63, v2
	v_mov_b32_e32 v64, v2
	v_mov_b32_e32 v65, v2
	v_mov_b32_e32 v66, v2
	v_mov_b32_e32 v67, v2
	v_mov_b32_e32 v68, v2
	v_mov_b32_e32 v69, v2
	v_mov_b32_e32 v70, v2
	v_mov_b32_e32 v71, v2
	v_mov_b32_e32 v72, v2
	v_mov_b32_e32 v73, v2
	v_mov_b32_e32 v82, v2
	v_mov_b32_e32 v83, v2
	v_mov_b32_e32 v84, v2
	v_mov_b32_e32 v85, v2
	v_mov_b32_e32 v86, v2
	v_mov_b32_e32 v87, v2
	v_mov_b32_e32 v88, v2
	v_mov_b32_e32 v89, v2
	v_mov_b32_e32 v98, v2
	v_mov_b32_e32 v99, v2
	v_mov_b32_e32 v100, v2
	v_mov_b32_e32 v101, v2
	v_mov_b32_e32 v102, v2
	v_mov_b32_e32 v103, v2
	v_mov_b32_e32 v104, v2
	v_mov_b32_e32 v105, v2
	v_mov_b32_e32 v114, v2
	v_mov_b32_e32 v115, v2
	v_mov_b32_e32 v116, v2
	v_mov_b32_e32 v117, v2
	v_mov_b32_e32 v118, v2
	v_mov_b32_e32 v119, v2
	v_mov_b32_e32 v120, v2
	v_mov_b32_e32 v121, v2
	v_mov_b32_e32 v74, v2
	v_mov_b32_e32 v75, v2
	v_mov_b32_e32 v76, v2
	v_mov_b32_e32 v77, v2
	v_mov_b32_e32 v78, v2
	v_mov_b32_e32 v79, v2
	v_mov_b32_e32 v80, v2
	v_mov_b32_e32 v81, v2
	v_mov_b32_e32 v90, v2
	v_mov_b32_e32 v91, v2
	v_mov_b32_e32 v92, v2
	v_mov_b32_e32 v93, v2
	v_mov_b32_e32 v94, v2
	v_mov_b32_e32 v95, v2
	v_mov_b32_e32 v96, v2
	v_mov_b32_e32 v97, v2
	v_mov_b32_e32 v106, v2
	v_mov_b32_e32 v107, v2
	v_mov_b32_e32 v108, v2
	v_mov_b32_e32 v109, v2
	v_mov_b32_e32 v110, v2
	v_mov_b32_e32 v111, v2
	v_mov_b32_e32 v112, v2
	v_mov_b32_e32 v113, v2
	v_mov_b32_e32 v126, v2
	v_mov_b32_e32 v127, v2
	v_mov_b32_e32 v128, v2
	v_mov_b32_e32 v129, v2
	v_mov_b32_e32 v122, v2
	v_mov_b32_e32 v123, v2
	v_mov_b32_e32 v124, v2
	v_mov_b32_e32 v125, v2
	s_nop 0

.LBB0_996:
	s_ashr_i32 s56, s50, 1
	s_ashr_i32 s63, s62, 31
	s_ashr_i32 s57, s56, 31
	s_lshl_b64 s[18:19], s[62:63], 19
	s_lshl_b64 s[56:57], s[56:57], 8
	s_add_u32 s18, s42, s18
	s_addc_u32 s19, s43, s19
	s_add_u32 s60, s18, s56
	s_addc_u32 s61, s19, s57
	s_ashr_i32 s51, s50, 31
	s_lshl_b64 s[18:19], s[50:51], 16
	s_add_u32 s56, s23, s18
	v_mov_b32_e32 v157, 0
	s_addc_u32 s57, s36, s19
	s_andn2_b64 vcc, exec, s[46:47]
	s_cbranch_vccnz .LBB0_1000
	s_and_b64 s[18:19], s[40:41], exec
	s_cselect_b32 s51, s61, s27
	s_cselect_b32 s63, s60, s26
	s_cselect_b32 s78, s57, s3
	s_cselect_b32 s79, s56, s2
	s_add_u32 s80, s26, 0x100
	s_addc_u32 s81, s27, 0
	s_add_u32 s82, s2, 0x100
	v_mov_b32_e32 v2, 0
	s_addc_u32 s83, s3, 0
	s_mov_b32 s2, 0
	v_mov_b32_e32 v3, v2
	v_mov_b32_e32 v4, v2
	v_mov_b32_e32 v5, v2
	v_mov_b32_e32 v78, v2
	v_mov_b32_e32 v79, v2
	v_mov_b32_e32 v80, v2
	v_mov_b32_e32 v81, v2
	v_mov_b32_e32 v10, v2
	v_mov_b32_e32 v11, v2
	v_mov_b32_e32 v12, v2
	v_mov_b32_e32 v13, v2
	v_mov_b32_e32 v90, v2
	v_mov_b32_e32 v91, v2
	v_mov_b32_e32 v92, v2
	v_mov_b32_e32 v93, v2
	v_mov_b32_e32 v18, v2
	v_mov_b32_e32 v19, v2
	v_mov_b32_e32 v20, v2
	v_mov_b32_e32 v21, v2
	v_mov_b32_e32 v102, v2
	v_mov_b32_e32 v103, v2
	v_mov_b32_e32 v104, v2
	v_mov_b32_e32 v105, v2
	v_mov_b32_e32 v26, v2
	v_mov_b32_e32 v27, v2
	v_mov_b32_e32 v28, v2
	v_mov_b32_e32 v29, v2
	v_mov_b32_e32 v114, v2
	v_mov_b32_e32 v115, v2
	v_mov_b32_e32 v116, v2
	v_mov_b32_e32 v117, v2
	v_mov_b32_e32 v6, v2
	v_mov_b32_e32 v7, v2
	v_mov_b32_e32 v8, v2
	v_mov_b32_e32 v9, v2
	v_mov_b32_e32 v82, v2
	v_mov_b32_e32 v83, v2
	v_mov_b32_e32 v84, v2
	v_mov_b32_e32 v85, v2
	v_mov_b32_e32 v14, v2
	v_mov_b32_e32 v15, v2
	v_mov_b32_e32 v16, v2
	v_mov_b32_e32 v17, v2
	v_mov_b32_e32 v94, v2
	v_mov_b32_e32 v95, v2
	v_mov_b32_e32 v96, v2
	v_mov_b32_e32 v97, v2
	v_mov_b32_e32 v22, v2
	v_mov_b32_e32 v23, v2
	v_mov_b32_e32 v24, v2
	v_mov_b32_e32 v25, v2
	v_mov_b32_e32 v106, v2
	v_mov_b32_e32 v107, v2
	v_mov_b32_e32 v108, v2
	v_mov_b32_e32 v109, v2
	v_mov_b32_e32 v30, v2
	v_mov_b32_e32 v31, v2
	v_mov_b32_e32 v32, v2
	v_mov_b32_e32 v33, v2
	v_mov_b32_e32 v118, v2
	v_mov_b32_e32 v119, v2
	v_mov_b32_e32 v120, v2
	v_mov_b32_e32 v121, v2
	v_mov_b32_e32 v34, v2
	v_mov_b32_e32 v35, v2
	v_mov_b32_e32 v36, v2
	v_mov_b32_e32 v37, v2
	v_mov_b32_e32 v126, v2
	v_mov_b32_e32 v127, v2
	v_mov_b32_e32 v128, v2
	v_mov_b32_e32 v129, v2
	v_mov_b32_e32 v42, v2
	v_mov_b32_e32 v43, v2
	v_mov_b32_e32 v44, v2
	v_mov_b32_e32 v45, v2
	v_mov_b32_e32 v134, v2
	v_mov_b32_e32 v135, v2
	v_mov_b32_e32 v136, v2
	v_mov_b32_e32 v137, v2
	v_mov_b32_e32 v50, v2
	v_mov_b32_e32 v51, v2
	v_mov_b32_e32 v52, v2
	v_mov_b32_e32 v53, v2
	v_mov_b32_e32 v142, v2
	v_mov_b32_e32 v143, v2
	v_mov_b32_e32 v144, v2
	v_mov_b32_e32 v145, v2
	v_mov_b32_e32 v58, v2
	v_mov_b32_e32 v59, v2
	v_mov_b32_e32 v60, v2
	v_mov_b32_e32 v61, v2
	v_mov_b32_e32 v150, v2
	v_mov_b32_e32 v151, v2
	v_mov_b32_e32 v152, v2
	v_mov_b32_e32 v153, v2
	v_mov_b32_e32 v38, v2
	v_mov_b32_e32 v39, v2
	v_mov_b32_e32 v40, v2
	v_mov_b32_e32 v41, v2
	v_mov_b32_e32 v130, v2
	v_mov_b32_e32 v131, v2
	v_mov_b32_e32 v132, v2
	v_mov_b32_e32 v133, v2
	v_mov_b32_e32 v46, v2
	v_mov_b32_e32 v47, v2
	v_mov_b32_e32 v48, v2
	v_mov_b32_e32 v49, v2
	v_mov_b32_e32 v138, v2
	v_mov_b32_e32 v139, v2
	v_mov_b32_e32 v140, v2
	v_mov_b32_e32 v141, v2
	v_mov_b32_e32 v54, v2
	v_mov_b32_e32 v55, v2
	v_mov_b32_e32 v56, v2
	v_mov_b32_e32 v57, v2
	v_mov_b32_e32 v146, v2
	v_mov_b32_e32 v147, v2
	v_mov_b32_e32 v148, v2
	v_mov_b32_e32 v149, v2
	v_mov_b32_e32 v62, v2
	v_mov_b32_e32 v63, v2
	v_mov_b32_e32 v64, v2
	v_mov_b32_e32 v65, v2
	v_mov_b32_e32 v154, v2
	v_mov_b32_e32 v155, v2
	v_mov_b32_e32 v156, v2
	v_mov_b32_e32 v157, v2
	s_nop 0

.LBB0_1492:
	s_ashr_i32 s73, s72, 31
	s_lshl_b64 s[0:1], s[72:73], 21
	s_add_u32 s2, s16, s0
	s_addc_u32 s3, s17, s1
	s_ashr_i32 s61, s60, 31
	s_lshl_b64 s[0:1], s[60:61], 21
	s_add_u32 s0, s21, s0
	v_mov_b32_e32 v141, 0
	s_addc_u32 s1, s22, s1
	s_andn2_b64 vcc, exec, s[54:55]
	s_waitcnt lgkmcnt(0)
	s_cbranch_vccnz .LBB0_1496
	s_and_b64 s[18:19], s[40:41], exec
	s_cselect_b32 s61, s3, s43
	s_cselect_b32 s73, s2, s42
	s_cselect_b32 s89, s1, s27
	s_cselect_b32 vcc_lo, s0, s26
	s_add_u32 vcc_hi, s42, 0x100
	s_addc_u32 s90, s43, 0
	s_add_u32 s91, s26, 0x100
	s_addc_u32 s92, s27, 0
	s_add_u32 s42, s42, 0x100080
	v_mov_b32_e32 v2, 0
	s_mov_b32 s24, s66
	s_mov_b32 s66, s97
	s_addc_u32 s43, s43, 0
	s_mov_b32 s18, 0
	v_mov_b32_e32 v3, v2
	v_mov_b32_e32 v4, v2
	v_mov_b32_e32 v5, v2
	v_mov_b32_e32 v6, v2
	v_mov_b32_e32 v7, v2
	v_mov_b32_e32 v8, v2
	v_mov_b32_e32 v9, v2
	v_mov_b32_e32 v18, v2
	v_mov_b32_e32 v19, v2
	v_mov_b32_e32 v20, v2
	v_mov_b32_e32 v21, v2
	v_mov_b32_e32 v22, v2
	v_mov_b32_e32 v23, v2
	v_mov_b32_e32 v24, v2
	v_mov_b32_e32 v25, v2
	v_mov_b32_e32 v34, v2
	v_mov_b32_e32 v35, v2
	v_mov_b32_e32 v36, v2
	v_mov_b32_e32 v37, v2
	v_mov_b32_e32 v38, v2
	v_mov_b32_e32 v39, v2
	v_mov_b32_e32 v40, v2
	v_mov_b32_e32 v41, v2
	v_mov_b32_e32 v50, v2
	v_mov_b32_e32 v51, v2
	v_mov_b32_e32 v52, v2
	v_mov_b32_e32 v53, v2
	v_mov_b32_e32 v54, v2
	v_mov_b32_e32 v55, v2
	v_mov_b32_e32 v56, v2
	v_mov_b32_e32 v57, v2
	v_mov_b32_e32 v10, v2
	v_mov_b32_e32 v11, v2
	v_mov_b32_e32 v12, v2
	v_mov_b32_e32 v13, v2
	v_mov_b32_e32 v14, v2
	v_mov_b32_e32 v15, v2
	v_mov_b32_e32 v16, v2
	v_mov_b32_e32 v17, v2
	v_mov_b32_e32 v26, v2
	v_mov_b32_e32 v27, v2
	v_mov_b32_e32 v28, v2
	v_mov_b32_e32 v29, v2
	v_mov_b32_e32 v30, v2
	v_mov_b32_e32 v31, v2
	v_mov_b32_e32 v32, v2
	v_mov_b32_e32 v33, v2
	v_mov_b32_e32 v42, v2
	v_mov_b32_e32 v43, v2
	v_mov_b32_e32 v44, v2
	v_mov_b32_e32 v45, v2
	v_mov_b32_e32 v46, v2
	v_mov_b32_e32 v47, v2
	v_mov_b32_e32 v48, v2
	v_mov_b32_e32 v49, v2
	v_mov_b32_e32 v58, v2
	v_mov_b32_e32 v59, v2
	v_mov_b32_e32 v60, v2
	v_mov_b32_e32 v61, v2
	v_mov_b32_e32 v62, v2
	v_mov_b32_e32 v63, v2
	v_mov_b32_e32 v64, v2
	v_mov_b32_e32 v65, v2
	v_mov_b32_e32 v66, v2
	v_mov_b32_e32 v67, v2
	v_mov_b32_e32 v68, v2
	v_mov_b32_e32 v69, v2
	v_mov_b32_e32 v70, v2
	v_mov_b32_e32 v71, v2
	v_mov_b32_e32 v72, v2
	v_mov_b32_e32 v73, v2
	v_mov_b32_e32 v86, v2
	v_mov_b32_e32 v87, v2
	v_mov_b32_e32 v88, v2
	v_mov_b32_e32 v89, v2
	v_mov_b32_e32 v94, v2
	v_mov_b32_e32 v95, v2
	v_mov_b32_e32 v96, v2
	v_mov_b32_e32 v97, v2
	v_mov_b32_e32 v114, v2
	v_mov_b32_e32 v115, v2
	v_mov_b32_e32 v116, v2
	v_mov_b32_e32 v117, v2
	v_mov_b32_e32 v118, v2
	v_mov_b32_e32 v119, v2
	v_mov_b32_e32 v120, v2
	v_mov_b32_e32 v121, v2
	v_mov_b32_e32 v130, v2
	v_mov_b32_e32 v131, v2
	v_mov_b32_e32 v132, v2
	v_mov_b32_e32 v133, v2
	v_mov_b32_e32 v134, v2
	v_mov_b32_e32 v135, v2
	v_mov_b32_e32 v136, v2
	v_mov_b32_e32 v137, v2
	v_mov_b32_e32 v74, v2
	v_mov_b32_e32 v75, v2
	v_mov_b32_e32 v76, v2
	v_mov_b32_e32 v77, v2
	v_mov_b32_e32 v78, v2
	v_mov_b32_e32 v79, v2
	v_mov_b32_e32 v80, v2
	v_mov_b32_e32 v81, v2
	v_mov_b32_e32 v102, v2
	v_mov_b32_e32 v103, v2
	v_mov_b32_e32 v104, v2
	v_mov_b32_e32 v105, v2
	v_mov_b32_e32 v106, v2
	v_mov_b32_e32 v107, v2
	v_mov_b32_e32 v108, v2
	v_mov_b32_e32 v109, v2
	v_mov_b32_e32 v122, v2
	v_mov_b32_e32 v123, v2
	v_mov_b32_e32 v124, v2
	v_mov_b32_e32 v125, v2
	v_mov_b32_e32 v126, v2
	v_mov_b32_e32 v127, v2
	v_mov_b32_e32 v128, v2
	v_mov_b32_e32 v129, v2
	v_mov_b32_e32 v142, v2
	v_mov_b32_e32 v143, v2
	v_mov_b32_e32 v144, v2
	v_mov_b32_e32 v145, v2
	v_mov_b32_e32 v138, v2
	v_mov_b32_e32 v139, v2
	v_mov_b32_e32 v140, v2
	v_mov_b32_e32 v141, v2
	s_nop 0
